# static priority raise for the blockIdx>=256 workgroup half also during the odd-attention tile loop
# baseline (speedup 1.0000x reference)
.LBB0_425:
	v_mov_b32_e32 v52, v228
	s_mul_i32 s3, s5, 0x1800
	v_ashrrev_i32_e32 v16, 31, v52
	v_lshrrev_b32_e32 v16, 28, v16
	v_add_u32_e32 v16, v52, v16
	v_ashrrev_i32_e32 v124, 4, v16
	v_and_b32_e32 v56, -16, v16
	v_add_u32_e32 v16, 0x100, v52
	v_ashrrev_i32_e32 v17, 31, v16
	s_mul_hi_u32 s16, s4, 0x1800
	v_lshrrev_b32_e32 v17, 28, v17
	v_add_u32_e32 v18, 0x300, v52
	s_add_i32 s16, s16, s3
	s_mul_i32 s3, s4, 0x1800
	v_add_u32_e32 v17, v16, v17
	v_ashrrev_i32_e32 v19, 31, v18
	s_add_u32 s3, s44, s3
	v_and_b32_e32 v58, -16, v17
	v_lshrrev_b32_e32 v19, 28, v19
	s_addc_u32 s17, s45, s16
	s_lshl_b64 s[12:13], s[12:13], 1
	v_sub_u32_e32 v59, v16, v58
	v_add_u32_e32 v16, 0x200, v52
	v_add_u32_e32 v19, v18, v19
	s_add_u32 s16, s3, s12
	v_ashrrev_i32_e32 v126, 4, v17
	v_ashrrev_i32_e32 v17, 31, v16
	v_and_b32_e32 v62, -16, v19
	s_addc_u32 s17, s17, s13
	v_lshrrev_b32_e32 v17, 28, v17
	v_ashrrev_i32_e32 v130, 4, v19
	v_sub_u32_e32 v63, v18, v62
	v_mov_b64_e32 v[0:1], s[16:17]
	v_lshlrev_b32_e32 v26, 3, v59
	v_add_u32_e32 v17, v16, v17
	v_lshlrev_b32_e32 v18, 3, v63
	v_mad_i64_i32 v[20:21], s[16:17], s10, v130, 0
	v_mad_i64_i32 v[32:33], s[16:17], s10, v126, 0
	v_ashrrev_i32_e32 v27, 31, v26
	v_and_b32_e32 v60, -16, v17
	v_ashrrev_i32_e32 v19, 31, v18
	v_lshlrev_b64 v[28:29], 1, v[20:21]
	v_lshlrev_b64 v[48:49], 1, v[32:33]
	v_sub_u32_e32 v57, v52, v56
	v_ashrrev_i32_e32 v128, 4, v17
	v_sub_u32_e32 v61, v16, v60
	v_lshl_add_u64 v[20:21], s[8:9], 0, v[28:29]
	v_lshlrev_b64 v[132:133], 1, v[18:19]
	v_lshl_add_u64 v[32:33], s[8:9], 0, v[48:49]
	v_lshlrev_b64 v[136:137], 1, v[26:27]
	v_ashrrev_i32_e32 v53, 6, v52
	v_and_b32_e32 v55, 15, v52
	v_lshlrev_b32_e32 v24, 3, v57
	v_lshlrev_b32_e32 v16, 3, v61
	v_lshl_add_u64 v[18:19], v[20:21], 0, v[132:133]
	v_mad_i64_i32 v[20:21], s[16:17], s10, v128, 0
	v_lshl_add_u64 v[26:27], v[32:33], 0, v[136:137]
	v_mad_i64_i32 v[32:33], s[16:17], s10, v124, 0
	v_bfe_u32 v54, v52, 4, 2
	v_lshl_or_b32 v122, v53, 4, v55
	v_ashrrev_i32_e32 v25, 31, v24
	v_ashrrev_i32_e32 v17, 31, v16
	v_lshlrev_b64 v[30:31], 1, v[20:21]
	v_lshlrev_b64 v[50:51], 1, v[32:33]
	v_mad_i64_i32 v[0:1], s[16:17], v122, s28, v[0:1]
	v_lshlrev_b32_e32 v196, 4, v54
	v_lshl_add_u64 v[20:21], s[8:9], 0, v[30:31]
	v_lshlrev_b64 v[134:135], 1, v[16:17]
	v_lshl_add_u64 v[32:33], s[8:9], 0, v[50:51]
	v_lshlrev_b64 v[138:139], 1, v[24:25]
	v_lshl_add_u64 v[12:13], v[0:1], 0, v[196:197]
	v_lshl_add_u64 v[16:17], v[20:21], 0, v[134:135]
	v_lshl_add_u64 v[24:25], v[32:33], 0, v[138:139]
	global_load_dwordx4 v[0:3], v[12:13], off
	global_load_dwordx4 v[4:7], v[12:13], off offset:64
	global_load_dwordx4 v[8:11], v[12:13], off offset:128
	s_nop 0
	global_load_dwordx4 v[12:15], v[12:13], off offset:192
	s_nop 0
	global_load_dwordx4 v[20:23], v[18:19], off
	s_nop 0
	global_load_dwordx4 v[16:19], v[16:17], off
	s_nop 0
	global_load_dwordx4 v[36:39], v[26:27], off
	global_load_dwordx4 v[32:35], v[24:25], off
	v_lshl_add_u64 v[24:25], s[6:7], 0, v[28:29]
	v_lshl_add_u64 v[26:27], s[6:7], 0, v[30:31]
	v_lshl_add_u64 v[24:25], v[24:25], 0, v[132:133]
	v_lshl_add_u64 v[26:27], v[26:27], 0, v[134:135]
	global_load_dwordx4 v[44:47], v[24:25], off
	global_load_dwordx4 v[40:43], v[26:27], off
	v_lshl_add_u64 v[24:25], s[6:7], 0, v[48:49]
	v_lshl_add_u64 v[26:27], s[6:7], 0, v[50:51]
	v_lshl_add_u64 v[24:25], v[24:25], 0, v[136:137]
	v_lshl_add_u64 v[26:27], v[26:27], 0, v[138:139]
	global_load_dwordx4 v[28:31], v[24:25], off
	s_nop 0
	global_load_dwordx4 v[24:27], v[26:27], off
	s_add_u32 s3, s44, s14
	s_addc_u32 s14, s45, s15
	s_add_u32 s3, s3, s12
	s_addc_u32 s17, s14, s13
	v_lshlrev_b32_e32 v120, 3, v54
	v_bfe_u32 v50, v52, 2, 2
	s_movk_i32 s19, 0x120
	s_add_u32 s14, s3, 0x800
	v_lshl_or_b32 v48, v53, 5, v55
	v_or_b32_e32 v50, v120, v50
	v_lshlrev_b32_e32 v51, 3, v52
	v_mul_lo_u32 v129, v124, s19
	v_mul_lo_u32 v141, v126, s19
	v_mul_lo_u32 v143, v128, s19
	v_mul_lo_u32 v145, v130, s19
	s_movk_i32 s19, 0xa0
	s_addc_u32 s15, s17, 0
	v_sub_u32_e32 v49, v196, v120
	v_and_b32_e32 v51, 24, v51
	v_lshlrev_b32_e32 v140, 4, v57
	v_lshlrev_b32_e32 v142, 4, v59
	v_lshlrev_b32_e32 v144, 4, v61
	v_lshlrev_b32_e32 v146, 4, v63
	v_sub_u32_e32 v52, v129, v56
	v_sub_u32_e32 v53, v141, v58
	v_sub_u32_e32 v54, v143, v60
	v_sub_u32_e32 v56, v145, v62
	v_mul_u32_u24_e32 v55, 0x120, v55
	v_mul_lo_u32 v48, v48, s19
	v_mul_u32_u24_e32 v50, 0x110, v50
	v_mov_b32_e32 v104, v197
	v_mov_b32_e32 v105, v197
	v_mov_b32_e32 v106, v197
	v_mov_b32_e32 v107, v197
	s_add_u32 s16, s3, 0x1000
	v_add_u32_e32 v147, v52, v140
	v_add_u32_e32 v148, v53, v142
	v_add_u32_e32 v149, v54, v144
	v_add_u32_e32 v150, v56, v146
	v_add_u32_e32 v151, v196, v48
	v_add_u32_e32 v152, v51, v50
	v_add_u32_e32 v153, v196, v55
	v_add_u32_e32 v154, v49, v48
	v_mov_b64_e32 v[60:61], v[104:105]
	v_mov_b64_e32 v[72:73], v[104:105]
	v_mov_b64_e32 v[64:65], v[104:105]
	v_mov_b64_e32 v[48:49], v[104:105]
	v_mov_b64_e32 v[56:57], v[104:105]
	v_mov_b64_e32 v[88:89], v[104:105]
	v_mov_b64_e32 v[92:93], v[104:105]
	v_mov_b64_e32 v[110:111], v[106:107]
	v_mov_b64_e32 v[76:77], v[104:105]
	v_mov_b64_e32 v[84:85], v[104:105]
	v_mov_b64_e32 v[80:81], v[104:105]
	v_mov_b64_e32 v[52:53], v[104:105]
	v_mov_b64_e32 v[68:69], v[104:105]
	v_mov_b64_e32 v[100:101], v[104:105]
	v_mov_b64_e32 v[96:97], v[104:105]
	s_addc_u32 s17, s17, 0
	v_ashrrev_i32_e32 v123, 31, v122
	s_or_b32 s3, s18, s2
	s_sub_i32 s25, 1, s2
	s_add_i32 s26, s18, s2
	s_mov_b32 s28, 0
	v_mov_b32_e32 v155, 0xf149f2ca
	v_mov_b32_e32 v131, 0
	v_mov_b64_e32 v[62:63], v[106:107]
	v_mov_b64_e32 v[74:75], v[106:107]
	v_mov_b64_e32 v[66:67], v[106:107]
	v_mov_b64_e32 v[50:51], v[106:107]
	v_mov_b64_e32 v[58:59], v[106:107]
	v_mov_b64_e32 v[90:91], v[106:107]
	v_mov_b64_e32 v[94:95], v[106:107]
	v_mov_b64_e32 v[108:109], v[104:105]
	v_mov_b64_e32 v[78:79], v[106:107]
	v_mov_b64_e32 v[86:87], v[106:107]
	v_mov_b64_e32 v[82:83], v[106:107]
	v_mov_b64_e32 v[54:55], v[106:107]
	v_mov_b64_e32 v[70:71], v[106:107]
	v_mov_b64_e32 v[102:103], v[106:107]
	v_mov_b64_e32 v[98:99], v[106:107]
	v_mov_b32_e32 v121, 0
	v_mov_b32_e32 v156, 0xf149f2ca
	v_mul_lo_u32 v242, v124, s10
	v_mul_lo_u32 v243, v126, s10
	v_mul_lo_u32 v244, v128, s10
	v_mul_lo_u32 v245, v130, s10
	s_movk_i32 s34, 0xc00
	v_mul_lo_u32 v246, v124, s34
	v_mul_lo_u32 v247, v126, s34
	v_mul_lo_u32 v248, v128, s34
	v_mul_lo_u32 v249, v130, s34
	v_lshl_add_u32 v242, v242, 1, v138
	v_lshl_add_u32 v243, v243, 1, v136
	v_lshl_add_u32 v244, v244, 1, v134
	v_lshl_add_u32 v245, v245, 1, v132
	v_lshl_add_u32 v246, v246, 1, v138
	v_lshl_add_u32 v247, v247, 1, v136
	v_lshl_add_u32 v248, v248, 1, v134
	v_lshl_add_u32 v249, v249, 1, v132
	v_add_u32_e32 v238, v129, v140
	v_add_u32_e32 v239, v141, v142
	v_add_u32_e32 v240, v143, v144
	v_add_u32_e32 v241, v145, v146
	v_bfe_u32 v214, v228, 4, 2
	v_mul_u32_u24_e32 v214, 0x440, v214
	v_sub_u32_e32 v214, v152, v214
	v_readlane_b32 s34, v252, 0
	s_cmp_ge_u32 s34, 0x100
	s_cbranch_scc0 .Laprio
	s_setprio 1
.Laprio:
.LBB0_426:
	s_mov_b32 s32, 0x3e38aa3b
	s_barrier
	s_waitcnt vmcnt(0)
	ds_write_b128 v238, v[24:27]
	ds_write_b128 v239, v[28:31]
	s_add_i32 s27, s28, 1
	ds_write_b128 v240, v[40:43]
	s_cmp_ge_u32 s27, s3
	ds_write_b128 v241, v[44:47]
	ds_write_b128 v147, v[32:35] offset:18432
	ds_write_b128 v148, v[36:39] offset:18432
	ds_write_b128 v149, v[16:19] offset:18432
	ds_write_b128 v150, v[20:23] offset:18432
	s_waitcnt lgkmcnt(0)
	s_barrier
	ds_read_b128 v[198:201], v153
	ds_read_b128 v[202:205], v153 offset:4608
	ds_read_b128 v[206:209], v153 offset:9216
	ds_read_b128 v[210:213], v153 offset:13824
	ds_read_b128 v[216:219], v153 offset:64
	ds_read_b128 v[220:223], v153 offset:4672
	ds_read_b128 v[224:227], v153 offset:9280
	ds_read_b128 v[230:233], v153 offset:13888
	s_cbranch_scc1 .LBB0_430
	s_cmp_lt_u32 s27, s2
	s_mov_b32 s29, s27
	s_mov_b64 s[18:19], s[10:11]
	s_mov_b64 s[22:23], s[6:7]
	s_mov_b64 s[20:21], s[8:9]
	s_cbranch_scc1 .LBB0_429
	s_add_i32 s29, s25, s28
	s_mov_b64 s[18:19], 0xc00
	s_mov_b64 s[22:23], s[14:15]
	s_mov_b64 s[20:21], s[16:17]
